# G1: GEMM epilogue stores flat_store_* -> global_store_* (no lgkmcnt coupling), on top of M34
# speedup vs baseline: 1.0180x; 1.0018x over previous
.LBB0_116:
	v_mbcnt_lo_u32_b32 v137, -1, 0
	v_mbcnt_hi_u32_b32 v137, -1, v137
	s_lshl_b32 s0, s39, 8
	s_nop 0
	v_ashrrev_i32_e32 v136, 1, v137
	v_and_or_b32 v137, v137, 15, s81
	v_and_b32_e32 v136, -8, v136
	s_or_b32 s0, s0, s82
	v_lshl_add_u32 v142, s38, 8, v137
	v_mov_b64_e32 v[138:139], s[10:11]
	v_add_u32_e32 v136, s0, v136
	v_mad_i64_i32 v[138:139], s[0:1], v142, s29, v[138:139]
	v_ashrrev_i32_e32 v137, 31, v136
	s_movk_i32 s0, 0x300
	v_lshl_add_u64 v[138:139], v[136:137], 1, v[138:139]
	v_cmp_gt_i32_e32 vcc, s0, v136
	s_and_saveexec_b64 s[0:1], vcc
	s_cbranch_execz .LBB0_118
	v_cvt_pk_bf16_f32 v118, v118, v119
	v_cvt_pk_bf16_f32 v119, v120, v121
	v_cvt_pk_bf16_f32 v120, v114, v115
	v_cvt_pk_bf16_f32 v121, v116, v117
	global_store_dwordx4 v[138:139], v[118:121], off
.LBB0_118:
	s_or_b64 exec, exec, s[0:1]
	v_cmp_gt_i32_e64 s[0:1], s97, v136
	s_mov_b64 s[34:35], exec
	s_and_b64 s[26:27], s[34:35], s[0:1]
	s_mov_b32 s77, 0x5f00000
	v_mov_b64_e32 v[246:247], v[216:217]
	v_mov_b64_e32 v[248:249], v[218:219]
	v_mov_b32_e32 v218, 0x358637bd
	s_mov_b64 exec, s[26:27]
	s_cbranch_execz .LBB0_120
	v_cvt_pk_bf16_f32 v114, v126, v127
	v_cvt_pk_bf16_f32 v115, v128, v129
	v_cvt_pk_bf16_f32 v116, v122, v123
	v_cvt_pk_bf16_f32 v117, v124, v125
	global_store_dwordx4 v[138:139], v[114:117], off offset:256
.LBB0_120:
	s_or_b64 exec, exec, s[34:35]
	s_nop 0
	v_or_b32_e32 v116, 16, v142
	v_mov_b64_e32 v[114:115], s[10:11]
	v_mad_i64_i32 v[114:115], s[26:27], v116, s29, v[114:115]
	v_lshl_add_u64 v[114:115], v[136:137], 1, v[114:115]
	s_and_saveexec_b64 s[34:35], vcc
	s_cbranch_execz .LBB0_122
	v_cvt_pk_bf16_f32 v102, v102, v103
	v_cvt_pk_bf16_f32 v103, v104, v105
	v_cvt_pk_bf16_f32 v104, v98, v99
	v_cvt_pk_bf16_f32 v105, v100, v101
	global_store_dwordx4 v[114:115], v[102:105], off
.LBB0_122:
	s_or_b64 exec, exec, s[34:35]
	s_and_saveexec_b64 s[34:35], s[0:1]
	s_cbranch_execz .LBB0_124
	v_cvt_pk_bf16_f32 v98, v110, v111
	v_cvt_pk_bf16_f32 v99, v112, v113
	v_cvt_pk_bf16_f32 v100, v106, v107
	v_cvt_pk_bf16_f32 v101, v108, v109
	global_store_dwordx4 v[114:115], v[98:101], off offset:256
.LBB0_124:
	s_or_b64 exec, exec, s[34:35]
	s_nop 0
	v_or_b32_e32 v100, 32, v142
	v_mov_b64_e32 v[98:99], s[10:11]
	v_mad_i64_i32 v[98:99], s[26:27], v100, s29, v[98:99]
	v_lshl_add_u64 v[98:99], v[136:137], 1, v[98:99]
	s_and_saveexec_b64 s[34:35], vcc
	s_cbranch_execz .LBB0_126
	v_cvt_pk_bf16_f32 v86, v86, v87
	v_cvt_pk_bf16_f32 v87, v88, v89
	v_cvt_pk_bf16_f32 v88, v82, v83
	v_cvt_pk_bf16_f32 v89, v84, v85
	global_store_dwordx4 v[98:99], v[86:89], off
.LBB0_126:
	s_or_b64 exec, exec, s[34:35]
	s_and_saveexec_b64 s[34:35], s[0:1]
	s_cbranch_execz .LBB0_128
	v_cvt_pk_bf16_f32 v82, v94, v95
	v_cvt_pk_bf16_f32 v83, v96, v97
	v_cvt_pk_bf16_f32 v84, v90, v91
	v_cvt_pk_bf16_f32 v85, v92, v93
	global_store_dwordx4 v[98:99], v[82:85], off offset:256
.LBB0_128:
	s_or_b64 exec, exec, s[34:35]
	s_nop 0
	v_or_b32_e32 v84, 48, v142
	v_mov_b64_e32 v[82:83], s[10:11]
	v_mad_i64_i32 v[82:83], s[26:27], v84, s29, v[82:83]
	v_lshl_add_u64 v[82:83], v[136:137], 1, v[82:83]
	s_and_saveexec_b64 s[34:35], vcc
	s_cbranch_execz .LBB0_130
	v_cvt_pk_bf16_f32 v56, v56, v57
	v_cvt_pk_bf16_f32 v57, v58, v59
	v_cvt_pk_bf16_f32 v58, v48, v49
	v_cvt_pk_bf16_f32 v59, v50, v51
	global_store_dwordx4 v[82:83], v[56:59], off
.LBB0_130:
	s_or_b64 exec, exec, s[34:35]
	s_and_saveexec_b64 s[34:35], s[0:1]
	s_cbranch_execz .LBB0_132
	v_cvt_pk_bf16_f32 v48, v72, v73
	v_cvt_pk_bf16_f32 v49, v74, v75
	v_cvt_pk_bf16_f32 v50, v64, v65
	v_cvt_pk_bf16_f32 v51, v66, v67
	global_store_dwordx4 v[82:83], v[48:51], off offset:256
.LBB0_132:
	s_or_b64 exec, exec, s[34:35]
	s_nop 0
	v_add_u32_e32 v50, 0x80, v142
	v_mov_b64_e32 v[48:49], s[10:11]
	v_mad_i64_i32 v[48:49], s[26:27], v50, s29, v[48:49]
	v_lshl_add_u64 v[48:49], v[136:137], 1, v[48:49]
	s_and_saveexec_b64 s[34:35], vcc
	s_cbranch_execz .LBB0_134
	v_cvt_pk_bf16_f32 v50, v60, v61
	v_cvt_pk_bf16_f32 v51, v62, v63
	v_cvt_pk_bf16_f32 v52, v52, v53
	v_cvt_pk_bf16_f32 v53, v54, v55
	global_store_dwordx4 v[48:49], v[50:53], off
.LBB0_134:
	s_or_b64 exec, exec, s[34:35]
	s_and_saveexec_b64 s[34:35], s[0:1]
	s_cbranch_execz .LBB0_136
	v_cvt_pk_bf16_f32 v50, v76, v77
	v_cvt_pk_bf16_f32 v51, v78, v79
	v_cvt_pk_bf16_f32 v52, v68, v69
	v_cvt_pk_bf16_f32 v53, v70, v71
	global_store_dwordx4 v[48:49], v[50:53], off offset:256
.LBB0_136:
	s_or_b64 exec, exec, s[34:35]
	s_nop 0
	v_add_u32_e32 v50, 0x90, v142
	v_mov_b64_e32 v[48:49], s[10:11]
	v_mad_i64_i32 v[48:49], s[26:27], v50, s29, v[48:49]
	v_lshl_add_u64 v[48:49], v[136:137], 1, v[48:49]
	s_and_saveexec_b64 s[34:35], vcc
	s_cbranch_execz .LBB0_138
	v_cvt_pk_bf16_f32 v36, v36, v37
	v_cvt_pk_bf16_f32 v37, v38, v39
	v_cvt_pk_bf16_f32 v38, v32, v33
	v_cvt_pk_bf16_f32 v39, v34, v35
	global_store_dwordx4 v[48:49], v[36:39], off
.LBB0_138:
	s_or_b64 exec, exec, s[34:35]
	s_and_saveexec_b64 s[34:35], s[0:1]
	s_cbranch_execz .LBB0_140
	v_cvt_pk_bf16_f32 v32, v44, v45
	v_cvt_pk_bf16_f32 v33, v46, v47
	v_cvt_pk_bf16_f32 v34, v40, v41
	v_cvt_pk_bf16_f32 v35, v42, v43
	global_store_dwordx4 v[48:49], v[32:35], off offset:256
.LBB0_140:
	s_or_b64 exec, exec, s[34:35]
	s_nop 0
	v_add_u32_e32 v34, 0xa0, v142
	v_mov_b64_e32 v[32:33], s[10:11]
	v_mad_i64_i32 v[32:33], s[26:27], v34, s29, v[32:33]
	v_lshl_add_u64 v[32:33], v[136:137], 1, v[32:33]
	s_and_saveexec_b64 s[34:35], vcc
	s_cbranch_execz .LBB0_142
	v_cvt_pk_bf16_f32 v20, v20, v21
	v_cvt_pk_bf16_f32 v21, v22, v23
	v_cvt_pk_bf16_f32 v22, v16, v17
	v_cvt_pk_bf16_f32 v23, v18, v19
	global_store_dwordx4 v[32:33], v[20:23], off
.LBB0_142:
	s_or_b64 exec, exec, s[34:35]
	s_and_saveexec_b64 s[34:35], s[0:1]
	s_cbranch_execz .LBB0_144
	v_cvt_pk_bf16_f32 v16, v28, v29
	v_cvt_pk_bf16_f32 v17, v30, v31
	v_cvt_pk_bf16_f32 v18, v24, v25
	v_cvt_pk_bf16_f32 v19, v26, v27
	global_store_dwordx4 v[32:33], v[16:19], off offset:256

.LBB0_147:
	v_cvt_pk_bf16_f32 v4, v4, v5
	v_cvt_pk_bf16_f32 v5, v6, v7
	v_cvt_pk_bf16_f32 v6, v0, v1
	v_cvt_pk_bf16_f32 v7, v2, v3
	global_store_dwordx4 v[16:17], v[4:7], off
	s_or_b64 exec, exec, s[34:35]
	s_and_saveexec_b64 s[34:35], s[0:1]
	s_cbranch_execz .LBB0_146
.LBB0_148:
	v_cvt_pk_bf16_f32 v0, v12, v13
	v_cvt_pk_bf16_f32 v1, v14, v15
	v_cvt_pk_bf16_f32 v2, v8, v9
	v_cvt_pk_bf16_f32 v3, v10, v11
	global_store_dwordx4 v[16:17], v[0:3], off offset:256
	s_or_b64 exec, exec, s[34:35]
	s_and_b64 vcc, exec, s[36:37]
	s_mov_b64 s[0:1], -1
	s_cbranch_vccnz .LBB0_107

.LBB0_170:
	v_and_or_b32 v138, v132, 15, s78
	v_ashrrev_i32_e32 v132, 2, v132
	s_lshl_b32 s30, s15, 7
	v_and_b32_e32 v134, -4, v132
	v_add_u32_e32 v132, s26, v138
	s_ashr_i32 s31, s30, 31
	s_lshl_b64 s[62:63], s[18:19], 1
	v_ashrrev_i32_e32 v133, 31, v132
	s_add_u32 s34, s34, s62
	v_lshlrev_b64 v[140:141], 10, v[132:133]
	s_addc_u32 s35, s35, s63
	v_lshl_add_u64 v[140:141], s[4:5], 0, v[140:141]
	s_lshl_b64 s[30:31], s[30:31], 1
	v_ashrrev_i32_e32 v135, 31, v134
	v_lshl_add_u64 v[140:141], v[140:141], 0, s[30:31]
	s_mov_b32 s15, s19
	v_add_u32_e32 v142, s80, v134
	v_lshl_add_u64 v[140:141], v[140:141], 0, s[14:15]
	v_lshlrev_b64 v[134:135], 1, v[134:135]
	v_lshl_add_u64 v[140:141], v[140:141], 0, v[134:135]
	v_cvt_pk_bf16_f32 v122, v122, v123
	v_cvt_pk_bf16_f32 v123, v124, v125
	global_store_dwordx2 v[140:141], v[122:123], off
	v_cvt_pk_bf16_f32 v118, v118, v119
	v_cvt_pk_bf16_f32 v119, v120, v121
	v_ashrrev_i32_e32 v139, 31, v138
	global_store_dwordx2 v[140:141], v[118:119], off offset:32
	v_lshl_add_u64 v[138:139], v[138:139], 1, s[34:35]
	v_mad_i64_i32 v[118:119], s[26:27], s17, v142, 0
	v_lshl_add_u64 v[118:119], v[118:119], 1, v[138:139]
	s_lshl_b32 s18, s17, 1
	v_cvt_pk_bf16_f32 v122, v126, v127
	v_lshl_add_u64 v[120:121], v[118:119], 0, s[18:19]
	s_lshl_b32 s26, s17, 2
	s_mov_b32 s27, s19
	s_mul_i32 s34, s17, 6
	s_mov_b32 s35, s19
	v_cvt_pk_bf16_f32 v126, v128, v129
	global_store_short v[118:119], v122, off
	global_store_short_d16_hi v[120:121], v122, off
	v_lshl_add_u64 v[122:123], v[118:119], 0, s[26:27]
	v_lshl_add_u64 v[124:125], v[118:119], 0, s[34:35]
	global_store_short v[122:123], v126, off
	global_store_short_d16_hi v[124:125], v126, off
	v_cvt_pk_bf16_f32 v126, v114, v115
	v_add_u32_e32 v114, 16, v142
	v_mad_i64_i32 v[114:115], s[62:63], s17, v114, 0
	v_lshl_add_u64 v[114:115], v[114:115], 1, v[138:139]
	v_add_u32_e32 v138, 16, v132
	v_ashrrev_i32_e32 v139, 31, v138
	v_lshlrev_b64 v[138:139], 10, v[138:139]
	v_lshl_add_u64 v[138:139], s[4:5], 0, v[138:139]
	v_cvt_pk_bf16_f32 v133, v116, v117
	v_lshl_add_u64 v[116:117], v[114:115], 0, s[18:19]
	v_lshl_add_u64 v[138:139], v[138:139], 0, s[30:31]
	global_store_short v[114:115], v126, off
	global_store_short_d16_hi v[116:117], v126, off
	v_lshl_add_u64 v[126:127], v[114:115], 0, s[26:27]
	v_lshl_add_u64 v[128:129], v[114:115], 0, s[34:35]
	v_lshl_add_u64 v[138:139], v[138:139], 0, s[14:15]
	global_store_short v[126:127], v133, off
	global_store_short_d16_hi v[128:129], v133, off
	v_lshl_add_u64 v[138:139], v[138:139], 0, v[134:135]
	v_cvt_pk_bf16_f32 v102, v102, v103
	v_cvt_pk_bf16_f32 v103, v104, v105
	global_store_dwordx2 v[138:139], v[102:103], off
	v_cvt_pk_bf16_f32 v98, v98, v99
	v_cvt_pk_bf16_f32 v99, v100, v101
	global_store_dwordx2 v[138:139], v[98:99], off offset:32
	v_cvt_pk_bf16_f32 v98, v110, v111
	v_cvt_pk_bf16_f32 v99, v112, v113
	global_store_short v[118:119], v98, off offset:32
	global_store_short_d16_hi v[120:121], v98, off offset:32
	global_store_short v[122:123], v99, off offset:32
	global_store_short_d16_hi v[124:125], v99, off offset:32
	v_cvt_pk_bf16_f32 v98, v106, v107
	v_cvt_pk_bf16_f32 v99, v108, v109
	global_store_short v[114:115], v98, off offset:32
	global_store_short_d16_hi v[116:117], v98, off offset:32
	global_store_short v[126:127], v99, off offset:32
	global_store_short_d16_hi v[128:129], v99, off offset:32
	v_add_u32_e32 v98, 32, v132
	v_ashrrev_i32_e32 v99, 31, v98
	v_lshlrev_b64 v[98:99], 10, v[98:99]
	v_lshl_add_u64 v[98:99], s[4:5], 0, v[98:99]
	v_lshl_add_u64 v[98:99], v[98:99], 0, s[30:31]
	v_lshl_add_u64 v[98:99], v[98:99], 0, s[14:15]
	v_lshl_add_u64 v[98:99], v[98:99], 0, v[134:135]
	v_cvt_pk_bf16_f32 v86, v86, v87
	v_cvt_pk_bf16_f32 v87, v88, v89
	global_store_dwordx2 v[98:99], v[86:87], off
	v_cvt_pk_bf16_f32 v82, v82, v83
	v_cvt_pk_bf16_f32 v83, v84, v85
	global_store_dwordx2 v[98:99], v[82:83], off offset:32
	v_cvt_pk_bf16_f32 v82, v94, v95
	v_cvt_pk_bf16_f32 v83, v96, v97
	global_store_short v[118:119], v82, off offset:64
	global_store_short_d16_hi v[120:121], v82, off offset:64
	global_store_short v[122:123], v83, off offset:64
	global_store_short_d16_hi v[124:125], v83, off offset:64
	v_cvt_pk_bf16_f32 v82, v90, v91
	v_cvt_pk_bf16_f32 v83, v92, v93
	global_store_short v[114:115], v82, off offset:64
	global_store_short_d16_hi v[116:117], v82, off offset:64
	global_store_short v[126:127], v83, off offset:64
	global_store_short_d16_hi v[128:129], v83, off offset:64
	v_add_u32_e32 v82, 48, v132
	v_ashrrev_i32_e32 v83, 31, v82
	v_lshlrev_b64 v[82:83], 10, v[82:83]
	v_lshl_add_u64 v[82:83], s[4:5], 0, v[82:83]
	v_lshl_add_u64 v[82:83], v[82:83], 0, s[30:31]
	v_lshl_add_u64 v[82:83], v[82:83], 0, s[14:15]
	v_lshl_add_u64 v[82:83], v[82:83], 0, v[134:135]
	v_cvt_pk_bf16_f32 v52, v52, v53
	v_cvt_pk_bf16_f32 v53, v54, v55
	global_store_dwordx2 v[82:83], v[52:53], off
	v_cvt_pk_bf16_f32 v48, v48, v49
	v_cvt_pk_bf16_f32 v49, v50, v51
	global_store_dwordx2 v[82:83], v[48:49], off offset:32
	v_cvt_pk_bf16_f32 v48, v68, v69
	v_cvt_pk_bf16_f32 v49, v70, v71
	global_store_short v[118:119], v48, off offset:96
	global_store_short_d16_hi v[120:121], v48, off offset:96
	global_store_short v[122:123], v49, off offset:96
	global_store_short_d16_hi v[124:125], v49, off offset:96
	v_cvt_pk_bf16_f32 v48, v60, v61
	v_cvt_pk_bf16_f32 v49, v62, v63
	global_store_short v[114:115], v48, off offset:96
	global_store_short_d16_hi v[116:117], v48, off offset:96
	global_store_short v[126:127], v49, off offset:96
	global_store_short_d16_hi v[128:129], v49, off offset:96
	v_add_u32_e32 v48, 0x80, v132
	v_ashrrev_i32_e32 v49, 31, v48
	v_lshlrev_b64 v[48:49], 10, v[48:49]
	v_lshl_add_u64 v[48:49], s[4:5], 0, v[48:49]
	v_lshl_add_u64 v[48:49], v[48:49], 0, s[30:31]
	v_lshl_add_u64 v[48:49], v[48:49], 0, s[14:15]
	v_lshl_add_u64 v[48:49], v[48:49], 0, v[134:135]
	v_cvt_pk_bf16_f32 v50, v64, v65
	v_cvt_pk_bf16_f32 v51, v66, v67
	global_store_dwordx2 v[48:49], v[50:51], off
	v_cvt_pk_bf16_f32 v50, v56, v57
	v_cvt_pk_bf16_f32 v51, v58, v59
	global_store_dwordx2 v[48:49], v[50:51], off offset:32
	v_cvt_pk_bf16_f32 v48, v76, v77
	v_cvt_pk_bf16_f32 v49, v78, v79
	global_store_short v[118:119], v48, off offset:256
	global_store_short_d16_hi v[120:121], v48, off offset:256
	global_store_short v[122:123], v49, off offset:256
	global_store_short_d16_hi v[124:125], v49, off offset:256
	v_cvt_pk_bf16_f32 v48, v72, v73
	v_cvt_pk_bf16_f32 v49, v74, v75
	global_store_short v[114:115], v48, off offset:256
	global_store_short_d16_hi v[116:117], v48, off offset:256
	global_store_short v[126:127], v49, off offset:256
	global_store_short_d16_hi v[128:129], v49, off offset:256
	v_add_u32_e32 v48, 0x90, v132
	v_ashrrev_i32_e32 v49, 31, v48
	v_lshlrev_b64 v[48:49], 10, v[48:49]
	v_lshl_add_u64 v[48:49], s[4:5], 0, v[48:49]
	v_lshl_add_u64 v[48:49], v[48:49], 0, s[30:31]
	v_lshl_add_u64 v[48:49], v[48:49], 0, s[14:15]
	v_lshl_add_u64 v[48:49], v[48:49], 0, v[134:135]
	v_cvt_pk_bf16_f32 v36, v36, v37
	v_cvt_pk_bf16_f32 v37, v38, v39
	global_store_dwordx2 v[48:49], v[36:37], off
	v_cvt_pk_bf16_f32 v32, v32, v33
	v_cvt_pk_bf16_f32 v33, v34, v35
	global_store_dwordx2 v[48:49], v[32:33], off offset:32
	v_cvt_pk_bf16_f32 v32, v44, v45
	v_cvt_pk_bf16_f32 v33, v46, v47
	global_store_short v[118:119], v32, off offset:288
	global_store_short_d16_hi v[120:121], v32, off offset:288
	global_store_short v[122:123], v33, off offset:288
	global_store_short_d16_hi v[124:125], v33, off offset:288
	v_cvt_pk_bf16_f32 v32, v40, v41
	v_cvt_pk_bf16_f32 v33, v42, v43
	global_store_short v[114:115], v32, off offset:288
	global_store_short_d16_hi v[116:117], v32, off offset:288
	global_store_short v[126:127], v33, off offset:288
	global_store_short_d16_hi v[128:129], v33, off offset:288
	v_add_u32_e32 v32, 0xa0, v132
	v_ashrrev_i32_e32 v33, 31, v32
	v_lshlrev_b64 v[32:33], 10, v[32:33]
	v_lshl_add_u64 v[32:33], s[4:5], 0, v[32:33]
	v_lshl_add_u64 v[32:33], v[32:33], 0, s[30:31]
	v_lshl_add_u64 v[32:33], v[32:33], 0, s[14:15]
	v_lshl_add_u64 v[32:33], v[32:33], 0, v[134:135]
	v_cvt_pk_bf16_f32 v20, v20, v21
	v_cvt_pk_bf16_f32 v21, v22, v23
	global_store_dwordx2 v[32:33], v[20:21], off
	v_cvt_pk_bf16_f32 v16, v16, v17
	v_cvt_pk_bf16_f32 v17, v18, v19
	global_store_dwordx2 v[32:33], v[16:17], off offset:32
	v_cvt_pk_bf16_f32 v16, v28, v29
	v_cvt_pk_bf16_f32 v17, v30, v31
	global_store_short v[118:119], v16, off offset:320
	global_store_short_d16_hi v[120:121], v16, off offset:320
	global_store_short v[122:123], v17, off offset:320
	global_store_short_d16_hi v[124:125], v17, off offset:320
	v_cvt_pk_bf16_f32 v16, v24, v25
	v_cvt_pk_bf16_f32 v17, v26, v27
	global_store_short v[114:115], v16, off offset:320
	global_store_short_d16_hi v[116:117], v16, off offset:320
	global_store_short v[126:127], v17, off offset:320
	global_store_short_d16_hi v[128:129], v17, off offset:320
	v_add_u32_e32 v16, 0xb0, v132
	v_ashrrev_i32_e32 v17, 31, v16
	v_lshlrev_b64 v[16:17], 10, v[16:17]
	v_lshl_add_u64 v[16:17], s[4:5], 0, v[16:17]
	v_lshl_add_u64 v[16:17], v[16:17], 0, s[30:31]
	v_lshl_add_u64 v[16:17], v[16:17], 0, s[14:15]
	v_lshl_add_u64 v[16:17], v[16:17], 0, v[134:135]
	v_cvt_pk_bf16_f32 v4, v4, v5
	v_cvt_pk_bf16_f32 v5, v6, v7
	global_store_dwordx2 v[16:17], v[4:5], off
	v_cvt_pk_bf16_f32 v0, v0, v1
	v_cvt_pk_bf16_f32 v1, v2, v3
	global_store_dwordx2 v[16:17], v[0:1], off offset:32
	v_cvt_pk_bf16_f32 v0, v12, v13
	v_cvt_pk_bf16_f32 v1, v14, v15
	global_store_short v[118:119], v0, off offset:352
	global_store_short_d16_hi v[120:121], v0, off offset:352
	global_store_short v[122:123], v1, off offset:352
	global_store_short_d16_hi v[124:125], v1, off offset:352
	v_cvt_pk_bf16_f32 v0, v8, v9
	v_cvt_pk_bf16_f32 v1, v10, v11
	global_store_short v[114:115], v0, off offset:352
	global_store_short_d16_hi v[116:117], v0, off offset:352
	global_store_short v[126:127], v1, off offset:352
	global_store_short_d16_hi v[128:129], v1, off offset:352
	s_andn2_b64 vcc, exec, s[36:37]
	s_mov_b64 s[30:31], -1
	s_cbranch_vccnz .LBB0_157
	s_andn2_b64 vcc, exec, s[0:1]
	s_cbranch_vccnz .LBB0_156
	s_barrier
	s_branch .LBB0_156

.LBB0_237:
	s_lshl_b32 s6, s78, 8
	v_mbcnt_lo_u32_b32 v141, -1, 0
	v_mbcnt_hi_u32_b32 v141, -1, v141
	s_add_i32 s6, s6, s71
	v_and_or_b32 v140, v141, 15, s6
	s_lshl_b32 s6, s77, 8
	v_ashrrev_i32_e32 v141, 1, v141
	s_or_b32 s6, s6, s81
	v_and_b32_e32 v141, -8, v141
	v_add_u32_e32 v142, s6, v141
	v_ashrrev_i32_e32 v141, 31, v140
	v_lshlrev_b64 v[144:145], 13, v[140:141]
	v_ashrrev_i32_e32 v143, 31, v142
	v_lshl_add_u64 v[144:145], s[4:5], 0, v[144:145]
	s_movk_i32 s6, 0x1000
	v_lshl_add_u64 v[144:145], v[142:143], 1, v[144:145]
	v_cmp_gt_i32_e32 vcc, s6, v142
	s_and_saveexec_b64 s[6:7], vcc
	s_cbranch_execz .LBB0_239
	v_max_f32_e32 v122, 0, v122
	v_max_f32_e32 v123, 0, v123
	v_max_f32_e32 v124, 0, v124
	v_max_f32_e32 v125, 0, v125
	v_max_f32_e32 v126, 0, v126
	v_max_f32_e32 v127, 0, v127
	v_max_f32_e32 v128, 0, v128
	v_max_f32_e32 v129, 0, v129
	v_pk_mul_f32 v[122:123], v[122:123], v[122:123]
	v_pk_mul_f32 v[124:125], v[124:125], v[124:125]
	v_pk_mul_f32 v[126:127], v[126:127], v[126:127]
	v_pk_mul_f32 v[128:129], v[128:129], v[128:129]
	v_cvt_pk_bf16_f32 v125, v124, v125
	v_cvt_pk_bf16_f32 v124, v122, v123
	v_cvt_pk_bf16_f32 v122, v126, v127
	v_cvt_pk_bf16_f32 v123, v128, v129
	s_cmp_lg_u64 s[36:37], 0
	s_cbranch_scc1 .Lm2_wb1
	global_store_dwordx4 v[144:145], v[122:125], off sc1
	s_branch .Lm2_j1
.Lm2_wb1:
	global_store_dwordx4 v[144:145], v[122:125], off
.Lm2_j1:
.LBB0_239:
	s_or_b64 exec, exec, s[6:7]
	v_cmp_gt_i32_e64 s[38:39], s24, v142
	s_and_saveexec_b64 s[6:7], s[38:39]
	s_cbranch_execz .LBB0_241
	v_max_f32_e32 v114, 0, v114
	v_max_f32_e32 v115, 0, v115
	v_max_f32_e32 v116, 0, v116
	v_max_f32_e32 v117, 0, v117
	v_max_f32_e32 v118, 0, v118
	v_max_f32_e32 v119, 0, v119
	v_max_f32_e32 v120, 0, v120
	v_max_f32_e32 v121, 0, v121
	v_pk_mul_f32 v[114:115], v[114:115], v[114:115]
	v_pk_mul_f32 v[116:117], v[116:117], v[116:117]
	v_pk_mul_f32 v[118:119], v[118:119], v[118:119]
	v_pk_mul_f32 v[120:121], v[120:121], v[120:121]
	v_cvt_pk_bf16_f32 v117, v116, v117
	v_cvt_pk_bf16_f32 v116, v114, v115
	v_cvt_pk_bf16_f32 v114, v118, v119
	v_cvt_pk_bf16_f32 v115, v120, v121
	s_cmp_lg_u64 s[36:37], 0
	s_cbranch_scc1 .Lm2_wb2
	global_store_dwordx4 v[144:145], v[114:117], off offset:256 sc1
	s_branch .Lm2_j2
.Lm2_wb2:
	global_store_dwordx4 v[144:145], v[114:117], off offset:256
.Lm2_j2:
.LBB0_241:
	s_or_b64 exec, exec, s[6:7]
	s_nop 0
	v_or_b32_e32 v114, 16, v140
	v_ashrrev_i32_e32 v115, 31, v114
	v_lshlrev_b64 v[114:115], 13, v[114:115]
	v_lshl_add_u64 v[114:115], s[4:5], 0, v[114:115]
	v_lshl_add_u64 v[114:115], v[142:143], 1, v[114:115]
	s_and_saveexec_b64 s[6:7], vcc
	s_cbranch_execz .LBB0_243
	v_max_f32_e32 v106, 0, v106
	v_max_f32_e32 v107, 0, v107
	v_max_f32_e32 v108, 0, v108
	v_max_f32_e32 v109, 0, v109
	v_max_f32_e32 v110, 0, v110
	v_max_f32_e32 v111, 0, v111
	v_max_f32_e32 v112, 0, v112
	v_max_f32_e32 v113, 0, v113
	v_pk_mul_f32 v[106:107], v[106:107], v[106:107]
	v_pk_mul_f32 v[108:109], v[108:109], v[108:109]
	v_pk_mul_f32 v[110:111], v[110:111], v[110:111]
	v_pk_mul_f32 v[112:113], v[112:113], v[112:113]
	v_cvt_pk_bf16_f32 v109, v108, v109
	v_cvt_pk_bf16_f32 v108, v106, v107
	v_cvt_pk_bf16_f32 v106, v110, v111
	v_cvt_pk_bf16_f32 v107, v112, v113
	s_cmp_lg_u64 s[36:37], 0
	s_cbranch_scc1 .Lm2_wb3
	global_store_dwordx4 v[114:115], v[106:109], off sc1
	s_branch .Lm2_j3
.Lm2_wb3:
	global_store_dwordx4 v[114:115], v[106:109], off
.Lm2_j3:
.LBB0_243:
	s_or_b64 exec, exec, s[6:7]
	s_and_saveexec_b64 s[6:7], s[38:39]
	s_cbranch_execz .LBB0_245
	v_max_f32_e32 v98, 0, v98
	v_max_f32_e32 v99, 0, v99
	v_max_f32_e32 v100, 0, v100
	v_max_f32_e32 v101, 0, v101
	v_max_f32_e32 v102, 0, v102
	v_max_f32_e32 v103, 0, v103
	v_max_f32_e32 v104, 0, v104
	v_max_f32_e32 v105, 0, v105
	v_pk_mul_f32 v[98:99], v[98:99], v[98:99]
	v_pk_mul_f32 v[100:101], v[100:101], v[100:101]
	v_pk_mul_f32 v[102:103], v[102:103], v[102:103]
	v_pk_mul_f32 v[104:105], v[104:105], v[104:105]
	v_cvt_pk_bf16_f32 v101, v100, v101
	v_cvt_pk_bf16_f32 v100, v98, v99
	v_cvt_pk_bf16_f32 v98, v102, v103
	v_cvt_pk_bf16_f32 v99, v104, v105
	s_cmp_lg_u64 s[36:37], 0
	s_cbranch_scc1 .Lm2_wb4
	global_store_dwordx4 v[114:115], v[98:101], off offset:256 sc1
	s_branch .Lm2_j4
.Lm2_wb4:
	global_store_dwordx4 v[114:115], v[98:101], off offset:256
.Lm2_j4:
.LBB0_245:
	s_or_b64 exec, exec, s[6:7]
	s_nop 0
	v_or_b32_e32 v98, 32, v140
	v_ashrrev_i32_e32 v99, 31, v98
	v_lshlrev_b64 v[98:99], 13, v[98:99]
	v_lshl_add_u64 v[98:99], s[4:5], 0, v[98:99]
	v_lshl_add_u64 v[98:99], v[142:143], 1, v[98:99]
	s_and_saveexec_b64 s[6:7], vcc
	s_cbranch_execz .LBB0_247
	v_max_f32_e32 v90, 0, v90
	v_max_f32_e32 v91, 0, v91
	v_max_f32_e32 v92, 0, v92
	v_max_f32_e32 v93, 0, v93
	v_max_f32_e32 v94, 0, v94
	v_max_f32_e32 v95, 0, v95
	v_max_f32_e32 v96, 0, v96
	v_max_f32_e32 v97, 0, v97
	v_pk_mul_f32 v[90:91], v[90:91], v[90:91]
	v_pk_mul_f32 v[92:93], v[92:93], v[92:93]
	v_pk_mul_f32 v[94:95], v[94:95], v[94:95]
	v_pk_mul_f32 v[96:97], v[96:97], v[96:97]
	v_cvt_pk_bf16_f32 v93, v92, v93
	v_cvt_pk_bf16_f32 v92, v90, v91
	v_cvt_pk_bf16_f32 v90, v94, v95
	v_cvt_pk_bf16_f32 v91, v96, v97
	s_cmp_lg_u64 s[36:37], 0
	s_cbranch_scc1 .Lm2_wb5
	global_store_dwordx4 v[98:99], v[90:93], off sc1
	s_branch .Lm2_j5
.Lm2_wb5:
	global_store_dwordx4 v[98:99], v[90:93], off
.Lm2_j5:
.LBB0_247:
	s_or_b64 exec, exec, s[6:7]
	s_and_saveexec_b64 s[6:7], s[38:39]
	s_cbranch_execz .LBB0_249
	v_max_f32_e32 v82, 0, v82
	v_max_f32_e32 v83, 0, v83
	v_max_f32_e32 v84, 0, v84
	v_max_f32_e32 v85, 0, v85
	v_max_f32_e32 v86, 0, v86
	v_max_f32_e32 v87, 0, v87
	v_max_f32_e32 v88, 0, v88
	v_max_f32_e32 v89, 0, v89
	v_pk_mul_f32 v[82:83], v[82:83], v[82:83]
	v_pk_mul_f32 v[84:85], v[84:85], v[84:85]
	v_pk_mul_f32 v[86:87], v[86:87], v[86:87]
	v_pk_mul_f32 v[88:89], v[88:89], v[88:89]
	v_cvt_pk_bf16_f32 v85, v84, v85
	v_cvt_pk_bf16_f32 v84, v82, v83
	v_cvt_pk_bf16_f32 v82, v86, v87
	v_cvt_pk_bf16_f32 v83, v88, v89
	s_cmp_lg_u64 s[36:37], 0
	s_cbranch_scc1 .Lm2_wb6
	global_store_dwordx4 v[98:99], v[82:85], off offset:256 sc1
	s_branch .Lm2_j6
.Lm2_wb6:
	global_store_dwordx4 v[98:99], v[82:85], off offset:256
.Lm2_j6:
.LBB0_249:
	s_or_b64 exec, exec, s[6:7]
	s_nop 0
	v_or_b32_e32 v82, 48, v140
	v_ashrrev_i32_e32 v83, 31, v82
	v_lshlrev_b64 v[82:83], 13, v[82:83]
	v_lshl_add_u64 v[82:83], s[4:5], 0, v[82:83]
	v_lshl_add_u64 v[82:83], v[142:143], 1, v[82:83]
	s_and_saveexec_b64 s[6:7], vcc
	s_cbranch_execz .LBB0_251
	v_max_f32_e32 v72, 0, v72
	v_max_f32_e32 v73, 0, v73
	v_max_f32_e32 v74, 0, v74
	v_max_f32_e32 v75, 0, v75
	v_max_f32_e32 v76, 0, v76
	v_max_f32_e32 v77, 0, v77
	v_max_f32_e32 v78, 0, v78
	v_max_f32_e32 v79, 0, v79
	v_pk_mul_f32 v[72:73], v[72:73], v[72:73]
	v_pk_mul_f32 v[74:75], v[74:75], v[74:75]
	v_pk_mul_f32 v[76:77], v[76:77], v[76:77]
	v_pk_mul_f32 v[78:79], v[78:79], v[78:79]
	v_cvt_pk_bf16_f32 v75, v74, v75
	v_cvt_pk_bf16_f32 v74, v72, v73
	v_cvt_pk_bf16_f32 v72, v76, v77
	v_cvt_pk_bf16_f32 v73, v78, v79
	s_cmp_lg_u64 s[36:37], 0
	s_cbranch_scc1 .Lm2_wb7
	global_store_dwordx4 v[82:83], v[72:75], off sc1
	s_branch .Lm2_j7
.Lm2_wb7:
	global_store_dwordx4 v[82:83], v[72:75], off
.Lm2_j7:
.LBB0_251:
	s_or_b64 exec, exec, s[6:7]
	s_and_saveexec_b64 s[6:7], s[38:39]
	s_cbranch_execz .LBB0_253
	v_max_f32_e32 v64, 0, v64
	v_max_f32_e32 v65, 0, v65
	v_max_f32_e32 v66, 0, v66
	v_max_f32_e32 v67, 0, v67
	v_max_f32_e32 v68, 0, v68
	v_max_f32_e32 v69, 0, v69
	v_max_f32_e32 v70, 0, v70
	v_max_f32_e32 v71, 0, v71
	v_pk_mul_f32 v[64:65], v[64:65], v[64:65]
	v_pk_mul_f32 v[66:67], v[66:67], v[66:67]
	v_pk_mul_f32 v[68:69], v[68:69], v[68:69]
	v_pk_mul_f32 v[70:71], v[70:71], v[70:71]
	v_cvt_pk_bf16_f32 v67, v66, v67
	v_cvt_pk_bf16_f32 v66, v64, v65
	v_cvt_pk_bf16_f32 v64, v68, v69
	v_cvt_pk_bf16_f32 v65, v70, v71
	s_cmp_lg_u64 s[36:37], 0
	s_cbranch_scc1 .Lm2_wb8
	global_store_dwordx4 v[82:83], v[64:67], off offset:256 sc1
	s_branch .Lm2_j8
.Lm2_wb8:
	global_store_dwordx4 v[82:83], v[64:67], off offset:256
.Lm2_j8:
.LBB0_253:
	s_or_b64 exec, exec, s[6:7]
	s_nop 0
	v_lshlrev_b64 v[64:65], 13, v[140:141]
	v_lshl_add_u64 v[64:65], s[4:5], 0, v[64:65]
	v_lshl_add_u64 v[64:65], v[142:143], 1, v[64:65]
	s_mov_b64 s[6:7], 0x100000
	v_lshl_add_u64 v[64:65], v[64:65], 0, s[6:7]
	s_and_saveexec_b64 s[6:7], vcc
	s_cbranch_execz .LBB0_255
	v_max_f32_e32 v56, 0, v56
	v_max_f32_e32 v57, 0, v57
	v_max_f32_e32 v58, 0, v58
	v_max_f32_e32 v59, 0, v59
	v_max_f32_e32 v60, 0, v60
	v_max_f32_e32 v61, 0, v61
	v_max_f32_e32 v62, 0, v62
	v_max_f32_e32 v63, 0, v63
	v_pk_mul_f32 v[56:57], v[56:57], v[56:57]
	v_pk_mul_f32 v[58:59], v[58:59], v[58:59]
	v_pk_mul_f32 v[60:61], v[60:61], v[60:61]
	v_pk_mul_f32 v[62:63], v[62:63], v[62:63]
	v_cvt_pk_bf16_f32 v59, v58, v59
	v_cvt_pk_bf16_f32 v58, v56, v57
	v_cvt_pk_bf16_f32 v56, v60, v61
	v_cvt_pk_bf16_f32 v57, v62, v63
	s_cmp_lg_u64 s[36:37], 0
	s_cbranch_scc1 .Lm2_wb9
	global_store_dwordx4 v[64:65], v[56:59], off sc1
	s_branch .Lm2_j9
.Lm2_wb9:
	global_store_dwordx4 v[64:65], v[56:59], off
.Lm2_j9:
.LBB0_255:
	s_or_b64 exec, exec, s[6:7]
	s_and_saveexec_b64 s[6:7], s[38:39]
	s_cbranch_execz .LBB0_257
	v_max_f32_e32 v48, 0, v48
	v_max_f32_e32 v49, 0, v49
	v_max_f32_e32 v50, 0, v50
	v_max_f32_e32 v51, 0, v51
	v_max_f32_e32 v52, 0, v52
	v_max_f32_e32 v53, 0, v53
	v_max_f32_e32 v54, 0, v54
	v_max_f32_e32 v55, 0, v55
	v_pk_mul_f32 v[48:49], v[48:49], v[48:49]
	v_pk_mul_f32 v[50:51], v[50:51], v[50:51]
	v_pk_mul_f32 v[52:53], v[52:53], v[52:53]
	v_pk_mul_f32 v[54:55], v[54:55], v[54:55]
	v_cvt_pk_bf16_f32 v51, v50, v51
	v_cvt_pk_bf16_f32 v50, v48, v49
	v_cvt_pk_bf16_f32 v48, v52, v53
	v_cvt_pk_bf16_f32 v49, v54, v55
	s_cmp_lg_u64 s[36:37], 0
	s_cbranch_scc1 .Lm2_wb10
	global_store_dwordx4 v[64:65], v[48:51], off offset:256 sc1
	s_branch .Lm2_j10
.Lm2_wb10:
	global_store_dwordx4 v[64:65], v[48:51], off offset:256
.Lm2_j10:
.LBB0_257:
	s_or_b64 exec, exec, s[6:7]
	s_nop 0
	v_lshlrev_b64 v[48:49], 13, v[140:141]
	v_lshl_add_u64 v[48:49], s[4:5], 0, v[48:49]
	v_lshl_add_u64 v[48:49], v[142:143], 1, v[48:49]
	s_mov_b64 s[6:7], 0x120000
	v_lshl_add_u64 v[48:49], v[48:49], 0, s[6:7]
	s_and_saveexec_b64 s[6:7], vcc
	s_cbranch_execz .LBB0_259
	v_max_f32_e32 v40, 0, v40
	v_max_f32_e32 v41, 0, v41
	v_max_f32_e32 v42, 0, v42
	v_max_f32_e32 v43, 0, v43
	v_max_f32_e32 v44, 0, v44
	v_max_f32_e32 v45, 0, v45
	v_max_f32_e32 v46, 0, v46
	v_max_f32_e32 v47, 0, v47
	v_pk_mul_f32 v[40:41], v[40:41], v[40:41]
	v_pk_mul_f32 v[42:43], v[42:43], v[42:43]
	v_pk_mul_f32 v[44:45], v[44:45], v[44:45]
	v_pk_mul_f32 v[46:47], v[46:47], v[46:47]
	v_cvt_pk_bf16_f32 v43, v42, v43
	v_cvt_pk_bf16_f32 v42, v40, v41
	v_cvt_pk_bf16_f32 v40, v44, v45
	v_cvt_pk_bf16_f32 v41, v46, v47
	s_cmp_lg_u64 s[36:37], 0
	s_cbranch_scc1 .Lm2_wb11
	global_store_dwordx4 v[48:49], v[40:43], off sc1
	s_branch .Lm2_j11
.Lm2_wb11:
	global_store_dwordx4 v[48:49], v[40:43], off
.Lm2_j11:
.LBB0_259:
	s_or_b64 exec, exec, s[6:7]
	s_and_saveexec_b64 s[6:7], s[38:39]
	s_cbranch_execz .LBB0_261
	v_max_f32_e32 v32, 0, v32
	v_max_f32_e32 v33, 0, v33
	v_max_f32_e32 v34, 0, v34
	v_max_f32_e32 v35, 0, v35
	v_max_f32_e32 v36, 0, v36
	v_max_f32_e32 v37, 0, v37
	v_max_f32_e32 v38, 0, v38
	v_max_f32_e32 v39, 0, v39
	v_pk_mul_f32 v[32:33], v[32:33], v[32:33]
	v_pk_mul_f32 v[34:35], v[34:35], v[34:35]
	v_pk_mul_f32 v[36:37], v[36:37], v[36:37]
	v_pk_mul_f32 v[38:39], v[38:39], v[38:39]
	v_cvt_pk_bf16_f32 v35, v34, v35
	v_cvt_pk_bf16_f32 v34, v32, v33
	v_cvt_pk_bf16_f32 v32, v36, v37
	v_cvt_pk_bf16_f32 v33, v38, v39
	s_cmp_lg_u64 s[36:37], 0
	s_cbranch_scc1 .Lm2_wb12
	global_store_dwordx4 v[48:49], v[32:35], off offset:256 sc1
	s_branch .Lm2_j12
.Lm2_wb12:
	global_store_dwordx4 v[48:49], v[32:35], off offset:256
.Lm2_j12:
.LBB0_261:
	s_or_b64 exec, exec, s[6:7]
	s_nop 0
	v_lshlrev_b64 v[32:33], 13, v[140:141]
	v_lshl_add_u64 v[32:33], s[4:5], 0, v[32:33]
	v_lshl_add_u64 v[32:33], v[142:143], 1, v[32:33]
	s_mov_b64 s[6:7], 0x140000
	v_lshl_add_u64 v[32:33], v[32:33], 0, s[6:7]
	s_and_saveexec_b64 s[6:7], vcc
	s_cbranch_execz .LBB0_263
	v_max_f32_e32 v24, 0, v24
	v_max_f32_e32 v25, 0, v25
	v_max_f32_e32 v26, 0, v26
	v_max_f32_e32 v27, 0, v27
	v_max_f32_e32 v28, 0, v28
	v_max_f32_e32 v29, 0, v29
	v_max_f32_e32 v30, 0, v30
	v_max_f32_e32 v31, 0, v31
	v_pk_mul_f32 v[24:25], v[24:25], v[24:25]
	v_pk_mul_f32 v[26:27], v[26:27], v[26:27]
	v_pk_mul_f32 v[28:29], v[28:29], v[28:29]
	v_pk_mul_f32 v[30:31], v[30:31], v[30:31]
	v_cvt_pk_bf16_f32 v27, v26, v27
	v_cvt_pk_bf16_f32 v26, v24, v25
	v_cvt_pk_bf16_f32 v24, v28, v29
	v_cvt_pk_bf16_f32 v25, v30, v31
	s_cmp_lg_u64 s[36:37], 0
	s_cbranch_scc1 .Lm2_wb13
	global_store_dwordx4 v[32:33], v[24:27], off sc1
	s_branch .Lm2_j13
.Lm2_wb13:
	global_store_dwordx4 v[32:33], v[24:27], off
.Lm2_j13:
.LBB0_263:
	s_or_b64 exec, exec, s[6:7]
	s_and_saveexec_b64 s[6:7], s[38:39]
	s_cbranch_execz .LBB0_265
	v_max_f32_e32 v16, 0, v16
	v_max_f32_e32 v17, 0, v17
	v_max_f32_e32 v18, 0, v18
	v_max_f32_e32 v19, 0, v19
	v_max_f32_e32 v20, 0, v20
	v_max_f32_e32 v21, 0, v21
	v_max_f32_e32 v22, 0, v22
	v_max_f32_e32 v23, 0, v23
	v_pk_mul_f32 v[16:17], v[16:17], v[16:17]
	v_pk_mul_f32 v[18:19], v[18:19], v[18:19]
	v_pk_mul_f32 v[20:21], v[20:21], v[20:21]
	v_pk_mul_f32 v[22:23], v[22:23], v[22:23]
	v_cvt_pk_bf16_f32 v19, v18, v19
	v_cvt_pk_bf16_f32 v18, v16, v17
	v_cvt_pk_bf16_f32 v16, v20, v21
	v_cvt_pk_bf16_f32 v17, v22, v23
	s_cmp_lg_u64 s[36:37], 0
	s_cbranch_scc1 .Lm2_wb14
	global_store_dwordx4 v[32:33], v[16:19], off offset:256 sc1
	s_branch .Lm2_j14
.Lm2_wb14:
	global_store_dwordx4 v[32:33], v[16:19], off offset:256

.LBB0_268:
	v_max_f32_e32 v8, 0, v8
	v_max_f32_e32 v9, 0, v9
	v_max_f32_e32 v10, 0, v10
	v_max_f32_e32 v11, 0, v11
	v_max_f32_e32 v12, 0, v12
	v_max_f32_e32 v13, 0, v13
	v_max_f32_e32 v14, 0, v14
	v_max_f32_e32 v15, 0, v15
	v_pk_mul_f32 v[8:9], v[8:9], v[8:9]
	v_pk_mul_f32 v[10:11], v[10:11], v[10:11]
	v_pk_mul_f32 v[12:13], v[12:13], v[12:13]
	v_pk_mul_f32 v[14:15], v[14:15], v[14:15]
	v_cvt_pk_bf16_f32 v11, v10, v11
	v_cvt_pk_bf16_f32 v10, v8, v9
	v_cvt_pk_bf16_f32 v8, v12, v13
	v_cvt_pk_bf16_f32 v9, v14, v15
	s_cmp_lg_u64 s[36:37], 0
	s_cbranch_scc1 .Lm2_wb15
	global_store_dwordx4 v[16:17], v[8:11], off sc1
	s_branch .Lm2_j15
.Lm2_wb15:
	global_store_dwordx4 v[16:17], v[8:11], off

.LBB0_269:
	v_max_f32_e32 v0, 0, v0
	v_max_f32_e32 v1, 0, v1
	v_max_f32_e32 v2, 0, v2
	v_max_f32_e32 v3, 0, v3
	v_max_f32_e32 v4, 0, v4
	v_max_f32_e32 v5, 0, v5
	v_max_f32_e32 v6, 0, v6
	v_max_f32_e32 v7, 0, v7
	v_pk_mul_f32 v[0:1], v[0:1], v[0:1]
	v_pk_mul_f32 v[2:3], v[2:3], v[2:3]
	v_pk_mul_f32 v[4:5], v[4:5], v[4:5]
	v_pk_mul_f32 v[6:7], v[6:7], v[6:7]
	v_cvt_pk_bf16_f32 v3, v2, v3
	v_cvt_pk_bf16_f32 v2, v0, v1
	v_cvt_pk_bf16_f32 v0, v4, v5
	v_cvt_pk_bf16_f32 v1, v6, v7
	s_cmp_lg_u64 s[36:37], 0
	s_cbranch_scc1 .Lm2_wb16
	global_store_dwordx4 v[16:17], v[0:3], off offset:256 sc1
	s_branch .Lm2_j16
.Lm2_wb16:
	global_store_dwordx4 v[16:17], v[0:3], off offset:256

.LBB0_392:
	v_mbcnt_lo_u32_b32 v141, -1, 0
	v_mbcnt_hi_u32_b32 v141, -1, v141
	s_lshl_b32 s0, s78, 8
	v_ashrrev_i32_e32 v140, 1, v141
	v_and_or_b32 v141, v141, 15, s80
	v_lshl_add_u32 v142, s77, 8, v141
	v_and_b32_e32 v140, -8, v140
	s_or_b32 s0, s0, s81
	v_ashrrev_i32_e32 v143, 31, v142
	v_add_u32_e32 v140, s0, v140
	v_lshlrev_b64 v[144:145], 11, v[142:143]
	v_ashrrev_i32_e32 v141, 31, v140
	v_lshl_add_u64 v[144:145], s[14:15], 0, v[144:145]
	v_lshl_add_u64 v[144:145], v[140:141], 1, v[144:145]
	v_cmp_gt_i32_e32 vcc, s90, v140
	s_and_saveexec_b64 s[0:1], vcc
	s_cbranch_execz .LBB0_394
	v_cvt_pk_bf16_f32 v126, v126, v127
	v_cvt_pk_bf16_f32 v127, v128, v129
	v_cvt_pk_bf16_f32 v128, v122, v123
	v_cvt_pk_bf16_f32 v129, v124, v125
	global_store_dwordx4 v[144:145], v[126:129], off sc1
.LBB0_394:
	s_or_b64 exec, exec, s[0:1]
	s_movk_i32 s0, 0x380
	v_cmp_gt_i32_e64 s[0:1], s0, v140
	s_and_saveexec_b64 s[6:7], s[0:1]
	s_cbranch_execz .LBB0_396
	v_cvt_pk_bf16_f32 v118, v118, v119
	v_cvt_pk_bf16_f32 v119, v120, v121
	v_cvt_pk_bf16_f32 v120, v110, v111
	v_cvt_pk_bf16_f32 v121, v112, v113
	global_store_dwordx4 v[144:145], v[118:121], off offset:256 sc1
.LBB0_396:
	s_or_b64 exec, exec, s[6:7]
	v_or_b32_e32 v110, 16, v142
	v_ashrrev_i32_e32 v111, 31, v110
	v_lshlrev_b64 v[110:111], 11, v[110:111]
	v_lshl_add_u64 v[110:111], s[14:15], 0, v[110:111]
	v_lshl_add_u64 v[110:111], v[140:141], 1, v[110:111]
	s_and_saveexec_b64 s[6:7], vcc
	s_cbranch_execz .LBB0_398
	v_cvt_pk_bf16_f32 v112, v114, v115
	v_cvt_pk_bf16_f32 v113, v116, v117
	v_cvt_pk_bf16_f32 v114, v106, v107
	v_cvt_pk_bf16_f32 v115, v108, v109
	global_store_dwordx4 v[110:111], v[112:115], off sc1
.LBB0_398:
	s_or_b64 exec, exec, s[6:7]
	s_and_saveexec_b64 s[6:7], s[0:1]
	s_cbranch_execz .LBB0_400
	v_cvt_pk_bf16_f32 v102, v102, v103
	v_cvt_pk_bf16_f32 v103, v104, v105
	v_cvt_pk_bf16_f32 v104, v94, v95
	v_cvt_pk_bf16_f32 v105, v96, v97
	global_store_dwordx4 v[110:111], v[102:105], off offset:256 sc1
.LBB0_400:
	s_or_b64 exec, exec, s[6:7]
	v_or_b32_e32 v94, 32, v142
	v_ashrrev_i32_e32 v95, 31, v94
	v_lshlrev_b64 v[94:95], 11, v[94:95]
	v_lshl_add_u64 v[94:95], s[14:15], 0, v[94:95]
	v_lshl_add_u64 v[94:95], v[140:141], 1, v[94:95]
	s_and_saveexec_b64 s[6:7], vcc
	s_cbranch_execz .LBB0_402
	v_cvt_pk_bf16_f32 v96, v98, v99
	v_cvt_pk_bf16_f32 v97, v100, v101
	v_cvt_pk_bf16_f32 v98, v90, v91
	v_cvt_pk_bf16_f32 v99, v92, v93
	global_store_dwordx4 v[94:95], v[96:99], off sc1
.LBB0_402:
	s_or_b64 exec, exec, s[6:7]
	s_and_saveexec_b64 s[6:7], s[0:1]
	s_cbranch_execz .LBB0_404
	v_cvt_pk_bf16_f32 v86, v86, v87
	v_cvt_pk_bf16_f32 v87, v88, v89
	v_cvt_pk_bf16_f32 v88, v76, v77
	v_cvt_pk_bf16_f32 v89, v78, v79
	global_store_dwordx4 v[94:95], v[86:89], off offset:256 sc1
.LBB0_404:
	s_or_b64 exec, exec, s[6:7]
	v_or_b32_e32 v76, 48, v142
	v_ashrrev_i32_e32 v77, 31, v76
	v_lshlrev_b64 v[76:77], 11, v[76:77]
	v_lshl_add_u64 v[76:77], s[14:15], 0, v[76:77]
	v_lshl_add_u64 v[76:77], v[140:141], 1, v[76:77]
	s_and_saveexec_b64 s[6:7], vcc
	s_cbranch_execz .LBB0_406
	v_cvt_pk_bf16_f32 v82, v82, v83
	v_cvt_pk_bf16_f32 v83, v84, v85
	v_cvt_pk_bf16_f32 v84, v72, v73
	v_cvt_pk_bf16_f32 v85, v74, v75
	global_store_dwordx4 v[76:77], v[82:85], off sc1
.LBB0_406:
	s_or_b64 exec, exec, s[6:7]
	s_and_saveexec_b64 s[6:7], s[0:1]
	s_cbranch_execz .LBB0_408
	v_cvt_pk_bf16_f32 v68, v68, v69
	v_cvt_pk_bf16_f32 v69, v70, v71
	v_cvt_pk_bf16_f32 v70, v64, v65
	v_cvt_pk_bf16_f32 v71, v66, v67
	global_store_dwordx4 v[76:77], v[68:71], off offset:256 sc1
.LBB0_408:
	s_or_b64 exec, exec, s[6:7]
	v_lshlrev_b64 v[64:65], 11, v[142:143]
	v_lshl_add_u64 v[64:65], s[14:15], 0, v[64:65]
	v_lshl_add_u64 v[64:65], v[140:141], 1, v[64:65]
	s_mov_b64 s[6:7], 0x40000
	v_lshl_add_u64 v[64:65], v[64:65], 0, s[6:7]
	s_and_saveexec_b64 s[6:7], vcc
	s_cbranch_execz .LBB0_410
	v_cvt_pk_bf16_f32 v60, v60, v61
	v_cvt_pk_bf16_f32 v61, v62, v63
	v_cvt_pk_bf16_f32 v62, v56, v57
	v_cvt_pk_bf16_f32 v63, v58, v59
	global_store_dwordx4 v[64:65], v[60:63], off sc1
.LBB0_410:
	s_or_b64 exec, exec, s[6:7]
	s_and_saveexec_b64 s[6:7], s[0:1]
	s_cbranch_execz .LBB0_412
	v_cvt_pk_bf16_f32 v52, v52, v53
	v_cvt_pk_bf16_f32 v53, v54, v55
	v_cvt_pk_bf16_f32 v54, v44, v45
	v_cvt_pk_bf16_f32 v55, v46, v47
	global_store_dwordx4 v[64:65], v[52:55], off offset:256 sc1
.LBB0_412:
	s_or_b64 exec, exec, s[6:7]
	v_lshlrev_b64 v[44:45], 11, v[142:143]
	v_lshl_add_u64 v[44:45], s[14:15], 0, v[44:45]
	v_lshl_add_u64 v[44:45], v[140:141], 1, v[44:45]
	s_mov_b64 s[6:7], 0x48000
	v_lshl_add_u64 v[44:45], v[44:45], 0, s[6:7]
	s_and_saveexec_b64 s[6:7], vcc
	s_cbranch_execz .LBB0_414
	v_cvt_pk_bf16_f32 v46, v48, v49
	v_cvt_pk_bf16_f32 v47, v50, v51
	v_cvt_pk_bf16_f32 v48, v40, v41
	v_cvt_pk_bf16_f32 v49, v42, v43
	global_store_dwordx4 v[44:45], v[46:49], off sc1
.LBB0_414:
	s_or_b64 exec, exec, s[6:7]
	s_and_saveexec_b64 s[6:7], s[0:1]
	s_cbranch_execz .LBB0_416
	v_cvt_pk_bf16_f32 v36, v36, v37
	v_cvt_pk_bf16_f32 v37, v38, v39
	v_cvt_pk_bf16_f32 v38, v28, v29
	v_cvt_pk_bf16_f32 v39, v30, v31
	global_store_dwordx4 v[44:45], v[36:39], off offset:256 sc1
.LBB0_416:
	s_or_b64 exec, exec, s[6:7]
	v_lshlrev_b64 v[28:29], 11, v[142:143]
	v_lshl_add_u64 v[28:29], s[14:15], 0, v[28:29]
	v_lshl_add_u64 v[28:29], v[140:141], 1, v[28:29]
	s_mov_b64 s[6:7], 0x50000
	v_lshl_add_u64 v[28:29], v[28:29], 0, s[6:7]
	s_and_saveexec_b64 s[6:7], vcc
	s_cbranch_execz .LBB0_418
	v_cvt_pk_bf16_f32 v30, v32, v33
	v_cvt_pk_bf16_f32 v31, v34, v35
	v_cvt_pk_bf16_f32 v32, v24, v25
	v_cvt_pk_bf16_f32 v33, v26, v27
	global_store_dwordx4 v[28:29], v[30:33], off sc1
.LBB0_418:
	s_or_b64 exec, exec, s[6:7]
	s_and_saveexec_b64 s[6:7], s[0:1]
	s_cbranch_execz .LBB0_420
	v_cvt_pk_bf16_f32 v20, v20, v21
	v_cvt_pk_bf16_f32 v21, v22, v23
	v_cvt_pk_bf16_f32 v22, v12, v13
	v_cvt_pk_bf16_f32 v23, v14, v15
	global_store_dwordx4 v[28:29], v[20:23], off offset:256 sc1

.LBB0_423:
	v_cvt_pk_bf16_f32 v14, v16, v17
	v_cvt_pk_bf16_f32 v15, v18, v19
	v_cvt_pk_bf16_f32 v16, v8, v9
	v_cvt_pk_bf16_f32 v17, v10, v11
	global_store_dwordx4 v[12:13], v[14:17], off sc1
	s_or_b64 exec, exec, s[6:7]
	s_and_saveexec_b64 s[6:7], s[0:1]
	s_cbranch_execz .LBB0_422
.LBB0_424:
	v_cvt_pk_bf16_f32 v4, v4, v5
	v_cvt_pk_bf16_f32 v5, v6, v7
	v_cvt_pk_bf16_f32 v6, v0, v1
	v_cvt_pk_bf16_f32 v7, v2, v3
	global_store_dwordx4 v[12:13], v[4:7], off offset:256 sc1
	s_or_b64 exec, exec, s[6:7]
	s_andn2_b64 vcc, exec, s[36:37]
	s_mov_b64 s[0:1], -1
	s_cbranch_vccnz .LBB0_385

.Lk0_e1:
	v_ashrrev_i32_e32 v140, 1, v141
	v_and_or_b32 v141, v141, 15, s64
	v_and_b32_e32 v140, -8, v140
	s_or_b32 s0, s0, s65
	v_lshl_add_u32 v146, s77, 8, v141
	v_mov_b64_e32 v[142:143], s[8:9]
	v_add_u32_e32 v140, s0, v140
	v_mad_i64_i32 v[142:143], s[0:1], v146, s24, v[142:143]
	v_ashrrev_i32_e32 v141, 31, v140
	s_movk_i32 s0, 0x7c0
	v_lshl_add_u64 v[142:143], v[140:141], 1, v[142:143]
	v_cmp_gt_i32_e32 vcc, s0, v140
	s_and_saveexec_b64 s[0:1], vcc
	s_cbranch_execz .LBB0_482
	v_cvt_pk_bf16_f32 v126, v126, v127
	v_cvt_pk_bf16_f32 v127, v128, v129
	v_cvt_pk_bf16_f32 v128, v122, v123
	v_cvt_pk_bf16_f32 v129, v124, v125
	s_cmp_lg_u64 s[36:37], 0
	s_cbranch_scc1 .Lm3_wb1
	global_store_dwordx4 v[142:143], v[126:129], off sc1
	s_branch .Lm3_j1
.Lm3_wb1:
	global_store_dwordx4 v[142:143], v[126:129], off
.Lm3_j1:
.LBB0_482:
	s_or_b64 exec, exec, s[0:1]
	s_movk_i32 s0, 0x740
	s_cmp_lg_u32 s101, 1
	s_cselect_b32 s0, s0, 0
	v_cmp_gt_i32_e64 s[0:1], s0, v140
	s_and_saveexec_b64 s[6:7], s[0:1]
	s_cbranch_execz .LBB0_484
	v_cvt_pk_bf16_f32 v118, v118, v119
	v_cvt_pk_bf16_f32 v119, v120, v121
	v_cvt_pk_bf16_f32 v120, v110, v111
	v_cvt_pk_bf16_f32 v121, v112, v113
	s_cmp_lg_u64 s[36:37], 0
	s_cbranch_scc1 .Lm3_wb2
	global_store_dwordx4 v[142:143], v[118:121], off offset:256 sc1
	s_branch .Lm3_j2
.Lm3_wb2:
	global_store_dwordx4 v[142:143], v[118:121], off offset:256
.Lm3_j2:
.LBB0_484:
	s_or_b64 exec, exec, s[6:7]
	v_or_b32_e32 v112, 16, v146
	v_mov_b64_e32 v[110:111], s[8:9]
	v_mad_i64_i32 v[110:111], s[6:7], v112, s24, v[110:111]
	v_lshl_add_u64 v[110:111], v[140:141], 1, v[110:111]
	s_and_saveexec_b64 s[6:7], vcc
	s_cbranch_execz .LBB0_486
	v_cvt_pk_bf16_f32 v112, v114, v115
	v_cvt_pk_bf16_f32 v113, v116, v117
	v_cvt_pk_bf16_f32 v114, v106, v107
	v_cvt_pk_bf16_f32 v115, v108, v109
	s_cmp_lg_u64 s[36:37], 0
	s_cbranch_scc1 .Lm3_wb3
	global_store_dwordx4 v[110:111], v[112:115], off sc1
	s_branch .Lm3_j3
.Lm3_wb3:
	global_store_dwordx4 v[110:111], v[112:115], off
.Lm3_j3:
.LBB0_486:
	s_or_b64 exec, exec, s[6:7]
	s_and_saveexec_b64 s[6:7], s[0:1]
	s_cbranch_execz .LBB0_488
	v_cvt_pk_bf16_f32 v102, v102, v103
	v_cvt_pk_bf16_f32 v103, v104, v105
	v_cvt_pk_bf16_f32 v104, v94, v95
	v_cvt_pk_bf16_f32 v105, v96, v97
	s_cmp_lg_u64 s[36:37], 0
	s_cbranch_scc1 .Lm3_wb4
	global_store_dwordx4 v[110:111], v[102:105], off offset:256 sc1
	s_branch .Lm3_j4
.Lm3_wb4:
	global_store_dwordx4 v[110:111], v[102:105], off offset:256
.Lm3_j4:
.LBB0_488:
	s_or_b64 exec, exec, s[6:7]
	v_or_b32_e32 v96, 32, v146
	v_mov_b64_e32 v[94:95], s[8:9]
	v_mad_i64_i32 v[94:95], s[6:7], v96, s24, v[94:95]
	v_lshl_add_u64 v[94:95], v[140:141], 1, v[94:95]
	s_and_saveexec_b64 s[6:7], vcc
	s_cbranch_execz .LBB0_490
	v_cvt_pk_bf16_f32 v96, v98, v99
	v_cvt_pk_bf16_f32 v97, v100, v101
	v_cvt_pk_bf16_f32 v98, v90, v91
	v_cvt_pk_bf16_f32 v99, v92, v93
	s_cmp_lg_u64 s[36:37], 0
	s_cbranch_scc1 .Lm3_wb5
	global_store_dwordx4 v[94:95], v[96:99], off sc1
	s_branch .Lm3_j5
.Lm3_wb5:
	global_store_dwordx4 v[94:95], v[96:99], off
.Lm3_j5:
.LBB0_490:
	s_or_b64 exec, exec, s[6:7]
	s_and_saveexec_b64 s[6:7], s[0:1]
	s_cbranch_execz .LBB0_492
	v_cvt_pk_bf16_f32 v86, v86, v87
	v_cvt_pk_bf16_f32 v87, v88, v89
	v_cvt_pk_bf16_f32 v88, v76, v77
	v_cvt_pk_bf16_f32 v89, v78, v79
	s_cmp_lg_u64 s[36:37], 0
	s_cbranch_scc1 .Lm3_wb6
	global_store_dwordx4 v[94:95], v[86:89], off offset:256 sc1
	s_branch .Lm3_j6
.Lm3_wb6:
	global_store_dwordx4 v[94:95], v[86:89], off offset:256
.Lm3_j6:
.LBB0_492:
	s_or_b64 exec, exec, s[6:7]
	v_or_b32_e32 v78, 48, v146
	v_mov_b64_e32 v[76:77], s[8:9]
	v_mad_i64_i32 v[76:77], s[6:7], v78, s24, v[76:77]
	v_lshl_add_u64 v[76:77], v[140:141], 1, v[76:77]
	s_and_saveexec_b64 s[6:7], vcc
	s_cbranch_execz .LBB0_494
	v_cvt_pk_bf16_f32 v82, v82, v83
	v_cvt_pk_bf16_f32 v83, v84, v85
	v_cvt_pk_bf16_f32 v84, v72, v73
	v_cvt_pk_bf16_f32 v85, v74, v75
	s_cmp_lg_u64 s[36:37], 0
	s_cbranch_scc1 .Lm3_wb7
	global_store_dwordx4 v[76:77], v[82:85], off sc1
	s_branch .Lm3_j7
.Lm3_wb7:
	global_store_dwordx4 v[76:77], v[82:85], off
.Lm3_j7:
.LBB0_494:
	s_or_b64 exec, exec, s[6:7]
	s_and_saveexec_b64 s[6:7], s[0:1]
	s_cbranch_execz .LBB0_496
	v_cvt_pk_bf16_f32 v68, v68, v69
	v_cvt_pk_bf16_f32 v69, v70, v71
	v_cvt_pk_bf16_f32 v70, v64, v65
	v_cvt_pk_bf16_f32 v71, v66, v67
	s_cmp_lg_u64 s[36:37], 0
	s_cbranch_scc1 .Lm3_wb8
	global_store_dwordx4 v[76:77], v[68:71], off offset:256 sc1
	s_branch .Lm3_j8
.Lm3_wb8:
	global_store_dwordx4 v[76:77], v[68:71], off offset:256
.Lm3_j8:
.LBB0_496:
	s_or_b64 exec, exec, s[6:7]
	v_add_u32_e32 v66, 0x80, v146
	v_mov_b64_e32 v[64:65], s[8:9]
	v_mad_i64_i32 v[64:65], s[6:7], v66, s24, v[64:65]
	v_lshl_add_u64 v[64:65], v[140:141], 1, v[64:65]
	s_and_saveexec_b64 s[6:7], vcc
	s_cbranch_execz .LBB0_498
	v_cvt_pk_bf16_f32 v60, v60, v61
	v_cvt_pk_bf16_f32 v61, v62, v63
	v_cvt_pk_bf16_f32 v62, v56, v57
	v_cvt_pk_bf16_f32 v63, v58, v59
	s_cmp_lg_u64 s[36:37], 0
	s_cbranch_scc1 .Lm3_wb9
	global_store_dwordx4 v[64:65], v[60:63], off sc1
	s_branch .Lm3_j9
.Lm3_wb9:
	global_store_dwordx4 v[64:65], v[60:63], off
.Lm3_j9:
.LBB0_498:
	s_or_b64 exec, exec, s[6:7]
	s_and_saveexec_b64 s[6:7], s[0:1]
	s_cbranch_execz .LBB0_500
	v_cvt_pk_bf16_f32 v52, v52, v53
	v_cvt_pk_bf16_f32 v53, v54, v55
	v_cvt_pk_bf16_f32 v54, v44, v45
	v_cvt_pk_bf16_f32 v55, v46, v47
	s_cmp_lg_u64 s[36:37], 0
	s_cbranch_scc1 .Lm3_wb10
	global_store_dwordx4 v[64:65], v[52:55], off offset:256 sc1
	s_branch .Lm3_j10
.Lm3_wb10:
	global_store_dwordx4 v[64:65], v[52:55], off offset:256
.Lm3_j10:
.LBB0_500:
	s_or_b64 exec, exec, s[6:7]
	v_add_u32_e32 v46, 0x90, v146
	v_mov_b64_e32 v[44:45], s[8:9]
	v_mad_i64_i32 v[44:45], s[6:7], v46, s24, v[44:45]
	v_lshl_add_u64 v[44:45], v[140:141], 1, v[44:45]
	s_and_saveexec_b64 s[6:7], vcc
	s_cbranch_execz .LBB0_502
	v_cvt_pk_bf16_f32 v46, v48, v49
	v_cvt_pk_bf16_f32 v47, v50, v51
	v_cvt_pk_bf16_f32 v48, v40, v41
	v_cvt_pk_bf16_f32 v49, v42, v43
	s_cmp_lg_u64 s[36:37], 0
	s_cbranch_scc1 .Lm3_wb11
	global_store_dwordx4 v[44:45], v[46:49], off sc1
	s_branch .Lm3_j11
.Lm3_wb11:
	global_store_dwordx4 v[44:45], v[46:49], off
.Lm3_j11:
.LBB0_502:
	s_or_b64 exec, exec, s[6:7]
	s_and_saveexec_b64 s[6:7], s[0:1]
	s_cbranch_execz .LBB0_504
	v_cvt_pk_bf16_f32 v36, v36, v37
	v_cvt_pk_bf16_f32 v37, v38, v39
	v_cvt_pk_bf16_f32 v38, v28, v29
	v_cvt_pk_bf16_f32 v39, v30, v31
	s_cmp_lg_u64 s[36:37], 0
	s_cbranch_scc1 .Lm3_wb12
	global_store_dwordx4 v[44:45], v[36:39], off offset:256 sc1
	s_branch .Lm3_j12
.Lm3_wb12:
	global_store_dwordx4 v[44:45], v[36:39], off offset:256
.Lm3_j12:
.LBB0_504:
	s_or_b64 exec, exec, s[6:7]
	v_add_u32_e32 v30, 0xa0, v146
	v_mov_b64_e32 v[28:29], s[8:9]
	v_mad_i64_i32 v[28:29], s[6:7], v30, s24, v[28:29]
	v_lshl_add_u64 v[28:29], v[140:141], 1, v[28:29]
	s_and_saveexec_b64 s[6:7], vcc
	s_cbranch_execz .LBB0_506
	v_cvt_pk_bf16_f32 v30, v32, v33
	v_cvt_pk_bf16_f32 v31, v34, v35
	v_cvt_pk_bf16_f32 v32, v24, v25
	v_cvt_pk_bf16_f32 v33, v26, v27
	s_cmp_lg_u64 s[36:37], 0
	s_cbranch_scc1 .Lm3_wb13
	global_store_dwordx4 v[28:29], v[30:33], off sc1
	s_branch .Lm3_j13
.Lm3_wb13:
	global_store_dwordx4 v[28:29], v[30:33], off
.Lm3_j13:
.LBB0_506:
	s_or_b64 exec, exec, s[6:7]
	s_and_saveexec_b64 s[6:7], s[0:1]
	s_cbranch_execz .LBB0_508
	v_cvt_pk_bf16_f32 v20, v20, v21
	v_cvt_pk_bf16_f32 v21, v22, v23
	v_cvt_pk_bf16_f32 v22, v12, v13
	v_cvt_pk_bf16_f32 v23, v14, v15
	s_cmp_lg_u64 s[36:37], 0
	s_cbranch_scc1 .Lm3_wb14
	global_store_dwordx4 v[28:29], v[20:23], off offset:256 sc1
	s_branch .Lm3_j14
.Lm3_wb14:
	global_store_dwordx4 v[28:29], v[20:23], off offset:256

.LBB0_511:
	v_cvt_pk_bf16_f32 v14, v16, v17
	v_cvt_pk_bf16_f32 v15, v18, v19
	v_cvt_pk_bf16_f32 v16, v8, v9
	v_cvt_pk_bf16_f32 v17, v10, v11
	s_cmp_lg_u64 s[36:37], 0
	s_cbranch_scc1 .Lm3_wb15
	global_store_dwordx4 v[12:13], v[14:17], off sc1
	s_branch .Lm3_j15
.Lm3_wb15:
	global_store_dwordx4 v[12:13], v[14:17], off

.LBB0_512:
	v_cvt_pk_bf16_f32 v4, v4, v5
	v_cvt_pk_bf16_f32 v5, v6, v7
	v_cvt_pk_bf16_f32 v6, v0, v1
	v_cvt_pk_bf16_f32 v7, v2, v3
	s_cmp_lg_u64 s[36:37], 0
	s_cbranch_scc1 .Lm3_wb16
	global_store_dwordx4 v[12:13], v[4:7], off offset:256 sc1
	s_branch .Lm3_j16
.Lm3_wb16:
	global_store_dwordx4 v[12:13], v[4:7], off offset:256
